# m2 plus grid-barrier L1 invalidate issued at arrival (overlaps the wait) instead of after the flag is observed
# speedup vs baseline: 1.0111x; 1.0094x over previous
; __device__ __forceinline__ int lane_id() { int l; asm volatile("v_mbcnt_lo_u32_b32 %0, -1, 0\n\tv_mbcnt_hi_u32_b32 %0, -1, %0" : "=v"(l)); return l; }
; __device__ __forceinline__ unsigned xb_ld(unsigned* p)              { return __hip_atomic_load(p, __ATOMIC_RELAXED, __HIP_MEMORY_SCOPE_AGENT); }
; __device__ __forceinline__ unsigned xb_add(unsigned* p, unsigned v) { return __hip_atomic_fetch_add(p, v, __ATOMIC_RELAXED, __HIP_MEMORY_SCOPE_AGENT); }
; #define XB_SPIN(cond, bar) do { unsigned _sp = 0; while (cond) { __builtin_amdgcn_s_sleep(1); \
;     if ((++_sp & 255u) == 0u) { if (xb_ld(&(bar)[XB_TMO])) break; if (_sp > XB_SPIN_CAP) { atomicAdd(&(bar)[XB_TMO], 1u); break; } } } } while (0)
; __device__ __forceinline__ void xcd_barrier(const XcdBarrier& b) {
;     ...
;     if (b.wave == 0 && lane_id() == 0) {
;         unsigned* bar = b.bar;
;         __builtin_amdgcn_s_waitcnt(0);
;         unsigned nloc = b.st[0], nx = b.st[1];
;         if (nloc == 0u) { xcd_barrier_complete(bar, b.x, nloc, nx); b.st[0] = nloc; b.st[1] = nx; }
;         const unsigned old = xb_add(&bar[XB_XSUB(b.x)], 1u);
;         const unsigned gen = old / nloc;
;         if (old + 1u == (gen + 1u) * nloc) {
;             __builtin_amdgcn_fence(__ATOMIC_RELEASE, "agent");
;             asm volatile("s_waitcnt vmcnt(0)" ::: "memory");
;             const unsigned og = xb_add(&bar[XB_TOP], 1u);
;             const unsigned tg = og / nx;
;             if (og + 1u == (tg + 1u) * nx) xb_add(&bar[XB_TOPGEN], 1u);
;             else XB_SPIN(xb_ld(&bar[XB_TOPGEN]) == tg, bar);
;             __builtin_amdgcn_fence(__ATOMIC_ACQUIRE, "agent");
;             xb_add(&bar[XB_XGEN(b.x)], 1u);
;             asm volatile("s_waitcnt vmcnt(0)" ::: "memory");
;         } else {
;             XB_SPIN(xb_ld(&bar[XB_XGEN(b.x)]) == gen, bar);
.LBB0_320:
	s_mov_b64 s[6:7], exec
	v_readlane_b32 s2, v254, 8
	s_lshl_b32 s2, s2, 8
	v_readlane_b32 s4, v254, 6
	v_mbcnt_lo_u32_b32 v1, s6, 0
	v_readlane_b32 s5, v254, 7
	s_add_u32 s4, s4, s2
	v_mbcnt_hi_u32_b32 v1, s7, v1
	s_addc_u32 s5, s5, 0
	v_cmp_eq_u32_e32 vcc, 0, v1
	s_and_saveexec_b64 s[14:15], vcc
	s_cbranch_execz .LBB0_322
	s_bcnt1_i32_b64 s2, s[6:7]
	v_mov_b32_e32 v3, 0x1000
	v_mov_b32_e32 v4, s2
	global_atomic_add v3, v3, v4, s[4:5] offset:1024 sc0
	buffer_inv sc1
.LBB0_322:
	s_or_b64 exec, exec, s[14:15]
	v_cvt_f32_u32_e32 v4, v2
	s_waitcnt vmcnt(1)
	v_readfirstlane_b32 s2, v3
	v_sub_u32_e32 v3, 0, v2
	v_rcp_iflag_f32_e32 v4, v4
	v_add_u32_e32 v5, s2, v1
	v_mul_f32_e32 v4, 0x4f7ffffe, v4
	v_cvt_u32_f32_e32 v4, v4
	v_mul_lo_u32 v1, v3, v4
	v_mul_hi_u32 v1, v4, v1
	v_add_u32_e32 v1, v4, v1
	v_mul_hi_u32 v1, v5, v1
	v_mul_lo_u32 v3, v1, v2
	v_sub_u32_e32 v3, v5, v3
	v_add_u32_e32 v4, 1, v1
	v_cmp_ge_u32_e32 vcc, v3, v2
	s_nop 1
	v_cndmask_b32_e32 v1, v1, v4, vcc
	v_sub_u32_e32 v4, v3, v2
	v_cndmask_b32_e32 v3, v3, v4, vcc
	v_add_u32_e32 v4, 1, v1
	v_cmp_ge_u32_e32 vcc, v3, v2
	v_add_u32_e32 v3, 1, v5
	s_nop 0
	v_cndmask_b32_e32 v1, v1, v4, vcc
	v_mul_lo_u32 v4, v2, v1
	v_add_u32_e32 v2, v4, v2
	v_cmp_ne_u32_e32 vcc, v3, v2
	s_and_saveexec_b64 s[6:7], vcc
	s_xor_b64 s[6:7], exec, s[6:7]
	s_cbranch_execz .LBB0_336
	s_waitcnt lgkmcnt(0)
	v_mov_b32_e32 v0, 0x2000
	global_load_dword v0, v0, s[4:5] offset:1024 sc1
	s_add_u32 s24, s4, 0x2400
	s_addc_u32 s25, s5, 0
	s_waitcnt vmcnt(0)
	v_cmp_eq_u32_e32 vcc, v0, v1
	s_and_saveexec_b64 s[14:15], vcc
	s_cbranch_execz .LBB0_335
	s_add_u32 s16, s10, 0x4200
	s_addc_u32 s17, s11, 0
	s_mov_b32 s8, 1
	s_mov_b64 s[36:37], 0
	v_mov_b32_e32 v0, 0
	s_branch .LBB0_326

; __device__ __forceinline__ unsigned xb_ld(unsigned* p)              { return __hip_atomic_load(p, __ATOMIC_RELAXED, __HIP_MEMORY_SCOPE_AGENT); }
; #define XB_SPIN(cond, bar) do { unsigned _sp = 0; while (cond) { __builtin_amdgcn_s_sleep(1); \
;     if ((++_sp & 255u) == 0u) { if (xb_ld(&(bar)[XB_TMO])) break; if (_sp > XB_SPIN_CAP) { atomicAdd(&(bar)[XB_TMO], 1u); break; } } } } while (0)
; __device__ __forceinline__ void xcd_barrier(const XcdBarrier& b) {
;     ...
;             XB_SPIN(xb_ld(&bar[XB_XGEN(b.x)]) == gen, bar);
;             __builtin_amdgcn_fence(__ATOMIC_ACQUIRE, "agent");
;             asm volatile("s_waitcnt vmcnt(0)" ::: "memory");
.LBB0_335:
	s_or_b64 exec, exec, s[14:15]
	s_waitcnt vmcnt(0)
	s_waitcnt vmcnt(0)

; __device__ __forceinline__ unsigned xb_add(unsigned* p, unsigned v) { return __hip_atomic_fetch_add(p, v, __ATOMIC_RELAXED, __HIP_MEMORY_SCOPE_AGENT); }
; __device__ __forceinline__ void xcd_barrier(const XcdBarrier& b) {
;     ...
;             __builtin_amdgcn_fence(__ATOMIC_ACQUIRE, "agent");
;             xb_add(&bar[XB_XGEN(b.x)], 1u);
;             asm volatile("s_waitcnt vmcnt(0)" ::: "memory");
.LBB0_353:
	s_or_b64 exec, exec, s[6:7]
	s_mov_b64 s[6:7], exec
	v_mbcnt_lo_u32_b32 v0, s6, 0
	v_mbcnt_hi_u32_b32 v0, s7, v0
	v_cmp_eq_u32_e32 vcc, 0, v0
	s_waitcnt vmcnt(0)
	s_and_saveexec_b64 s[14:15], vcc
	s_cbranch_execz .LBB0_355
	s_bcnt1_i32_b64 s2, s[6:7]
	v_mov_b32_e32 v0, 0x2000
	v_mov_b32_e32 v1, s2
	global_atomic_add v0, v1, s[4:5] offset:1024
.LBB0_355:
	s_or_b64 exec, exec, s[14:15]
	s_waitcnt vmcnt(0)

; __device__ __forceinline__ unsigned xb_add(unsigned* p, unsigned v) { return __hip_atomic_fetch_add(p, v, __ATOMIC_RELAXED, __HIP_MEMORY_SCOPE_AGENT); }
; __device__ __forceinline__ void xcd_barrier(const XcdBarrier& b) {
;     ...
;             __builtin_amdgcn_fence(__ATOMIC_ACQUIRE, "agent");
;             xb_add(&bar[XB_XGEN(b.x)], 1u);
;             asm volatile("s_waitcnt vmcnt(0)" ::: "memory");
.LBB0_495:
	s_or_b64 exec, exec, s[6:7]
	s_mov_b64 s[6:7], exec
	v_mbcnt_lo_u32_b32 v0, s6, 0
	v_mbcnt_hi_u32_b32 v0, s7, v0
	v_cmp_eq_u32_e32 vcc, 0, v0
	s_waitcnt vmcnt(0)
	s_and_saveexec_b64 s[14:15], vcc
	s_cbranch_execz .LBB0_497
	s_bcnt1_i32_b64 s2, s[6:7]
	v_mov_b32_e32 v0, 0x2000
	v_mov_b32_e32 v1, s2
	global_atomic_add v0, v1, s[4:5] offset:1024
.LBB0_497:
	s_or_b64 exec, exec, s[14:15]
	s_waitcnt vmcnt(0)

; __device__ __forceinline__ int lane_id() { int l; asm volatile("v_mbcnt_lo_u32_b32 %0, -1, 0\n\tv_mbcnt_hi_u32_b32 %0, -1, %0" : "=v"(l)); return l; }
; __device__ __forceinline__ unsigned xb_add(unsigned* p, unsigned v) { return __hip_atomic_fetch_add(p, v, __ATOMIC_RELAXED, __HIP_MEMORY_SCOPE_AGENT); }
; __device__ __forceinline__ XcdTok xcd_arrive(const XcdBarrier& b) {
;     XcdTok t; t.gen = 0u; t.tg = 0u; t.role = 0;
;     asm volatile("s_waitcnt vmcnt(0)" ::: "memory");
;     __syncthreads();
;     if (b.wave == 0 && lane_id() == 0) {
;         unsigned* bar = b.bar;
;         __builtin_amdgcn_s_waitcnt(0);
;         unsigned nloc = b.st[0], nx = b.st[1];
;         if (nloc == 0u) { xcd_barrier_complete(bar, b.x, nloc, nx); b.st[0] = nloc; b.st[1] = nx; }
;         const unsigned old = xb_add(&bar[XB_XSUB(b.x)], 1u);
;         t.gen = old / nloc;
;         if (old + 1u == (t.gen + 1u) * nloc) {
;             __builtin_amdgcn_fence(__ATOMIC_RELEASE, "agent");
;             asm volatile("s_waitcnt vmcnt(0)" ::: "memory");
;             const unsigned og = xb_add(&bar[XB_TOP], 1u);
;             t.tg = og / nx;
;             if (og + 1u == (t.tg + 1u) * nx) { xb_add(&bar[XB_TOPGEN], 1u); t.role = 2; } else t.role = 1;
;         }
.LBB0_558:
	s_mov_b64 s[6:7], exec
	v_mbcnt_lo_u32_b32 v2, s6, 0
	v_mbcnt_hi_u32_b32 v2, s7, v2
	v_cmp_eq_u32_e32 vcc, 0, v2
	s_and_saveexec_b64 s[4:5], vcc
	s_cbranch_execz .LBB0_560
	v_readlane_b32 s2, v254, 8
	s_lshl_b32 s2, s2, 8
	v_readlane_b32 s8, v254, 6
	v_readlane_b32 s9, v254, 7
	s_add_u32 s8, s8, s2
	s_addc_u32 s9, s9, 0
	s_bcnt1_i32_b64 s2, s[6:7]
	v_mov_b32_e32 v3, 0x1000
	v_mov_b32_e32 v4, s2
	global_atomic_add v3, v3, v4, s[8:9] offset:1024 sc0
	buffer_inv sc1
.LBB0_560:
	s_or_b64 exec, exec, s[4:5]
	v_cvt_f32_u32_e32 v4, v1
	s_waitcnt vmcnt(1)
	v_readfirstlane_b32 s2, v3
	s_mov_b64 s[6:7], 0
	v_mov_b32_e32 v79, 0
	v_rcp_iflag_f32_e32 v4, v4
	v_add_u32_e32 v2, s2, v2
	v_add_u32_e32 v5, 1, v2
	s_mov_b64 s[16:17], 0
	v_mul_f32_e32 v3, 0x4f7ffffe, v4
	v_cvt_u32_f32_e32 v3, v3
	v_sub_u32_e32 v4, 0, v1
	v_mul_lo_u32 v4, v4, v3
	v_mul_hi_u32 v4, v3, v4
	v_add_u32_e32 v3, v3, v4
	v_mul_hi_u32 v3, v2, v3
	v_mul_lo_u32 v4, v3, v1
	v_sub_u32_e32 v2, v2, v4
	v_add_u32_e32 v6, 1, v3
	v_cmp_ge_u32_e32 vcc, v2, v1
	v_sub_u32_e32 v4, v2, v1
	s_nop 0
	v_cndmask_b32_e32 v3, v3, v6, vcc
	v_cndmask_b32_e32 v2, v2, v4, vcc
	v_add_u32_e32 v4, 1, v3
	v_cmp_ge_u32_e32 vcc, v2, v1
	s_nop 1
	v_cndmask_b32_e32 v75, v3, v4, vcc
	v_mul_lo_u32 v2, v1, v75
	v_add_u32_e32 v1, v2, v1
	v_cmp_eq_u32_e32 vcc, v5, v1
	s_and_saveexec_b64 s[4:5], vcc
	s_cbranch_execz .LBB0_568
	s_mov_b64 s[6:7], exec
	buffer_wbl2 sc1
	s_waitcnt lgkmcnt(0)
	s_waitcnt vmcnt(0)
	v_mbcnt_lo_u32_b32 v1, s6, 0
	v_mbcnt_hi_u32_b32 v1, s7, v1
	v_cmp_eq_u32_e32 vcc, 0, v1
	s_and_saveexec_b64 s[16:17], vcc
	s_cbranch_execz .LBB0_563
	s_bcnt1_i32_b64 s2, s[6:7]
	v_mov_b32_e32 v2, 0x7000
	v_mov_b32_e32 v3, s2
	global_atomic_add v2, v2, v3, s[10:11] offset:1024 sc0

; __device__ __forceinline__ unsigned xb_ld(unsigned* p)              { return __hip_atomic_load(p, __ATOMIC_RELAXED, __HIP_MEMORY_SCOPE_AGENT); }
; #define XB_SPIN(cond, bar) do { unsigned _sp = 0; while (cond) { __builtin_amdgcn_s_sleep(1); \
;     if ((++_sp & 255u) == 0u) { if (xb_ld(&(bar)[XB_TMO])) break; if (_sp > XB_SPIN_CAP) { atomicAdd(&(bar)[XB_TMO], 1u); break; } } } } while (0)
; __device__ __forceinline__ void xcd_wait(const XcdBarrier& b, const XcdTok& t) {
;     ...
;         } else {
;             XB_SPIN(xb_ld(&bar[XB_XGEN(b.x)]) == t.gen, bar);
;             __builtin_amdgcn_fence(__ATOMIC_ACQUIRE, "agent");
;             asm volatile("s_waitcnt vmcnt(0)" ::: "memory");
.LBB0_593:
	s_or_b64 exec, exec, s[20:21]
	s_waitcnt vmcnt(0) lgkmcnt(0)
	s_waitcnt vmcnt(0)

; __device__ __forceinline__ int lane_id() { int l; asm volatile("v_mbcnt_lo_u32_b32 %0, -1, 0\n\tv_mbcnt_hi_u32_b32 %0, -1, %0" : "=v"(l)); return l; }
; __device__ __forceinline__ unsigned xb_ld(unsigned* p)              { return __hip_atomic_load(p, __ATOMIC_RELAXED, __HIP_MEMORY_SCOPE_AGENT); }
; __device__ __forceinline__ unsigned xb_add(unsigned* p, unsigned v) { return __hip_atomic_fetch_add(p, v, __ATOMIC_RELAXED, __HIP_MEMORY_SCOPE_AGENT); }
; #define XB_SPIN(cond, bar) do { unsigned _sp = 0; while (cond) { __builtin_amdgcn_s_sleep(1); \
;     if ((++_sp & 255u) == 0u) { if (xb_ld(&(bar)[XB_TMO])) break; if (_sp > XB_SPIN_CAP) { atomicAdd(&(bar)[XB_TMO], 1u); break; } } } } while (0)
; __device__ __forceinline__ void xcd_barrier(const XcdBarrier& b) {
;     ...
;     if (b.wave == 0 && lane_id() == 0) {
;         unsigned* bar = b.bar;
;         __builtin_amdgcn_s_waitcnt(0);
;         unsigned nloc = b.st[0], nx = b.st[1];
;         if (nloc == 0u) { xcd_barrier_complete(bar, b.x, nloc, nx); b.st[0] = nloc; b.st[1] = nx; }
;         const unsigned old = xb_add(&bar[XB_XSUB(b.x)], 1u);
;         const unsigned gen = old / nloc;
;         if (old + 1u == (gen + 1u) * nloc) {
;             __builtin_amdgcn_fence(__ATOMIC_RELEASE, "agent");
;             asm volatile("s_waitcnt vmcnt(0)" ::: "memory");
;             const unsigned og = xb_add(&bar[XB_TOP], 1u);
;             const unsigned tg = og / nx;
;             if (og + 1u == (tg + 1u) * nx) xb_add(&bar[XB_TOPGEN], 1u);
;             else XB_SPIN(xb_ld(&bar[XB_TOPGEN]) == tg, bar);
;             __builtin_amdgcn_fence(__ATOMIC_ACQUIRE, "agent");
;             xb_add(&bar[XB_XGEN(b.x)], 1u);
;             asm volatile("s_waitcnt vmcnt(0)" ::: "memory");
;         } else {
;             XB_SPIN(xb_ld(&bar[XB_XGEN(b.x)]) == gen, bar);
.LBB0_645:
	s_or_b64 exec, exec, s[14:15]
	v_cvt_f32_u32_e32 v4, v2
	s_waitcnt vmcnt(1)
	v_readfirstlane_b32 s2, v3
	v_sub_u32_e32 v3, 0, v2
	v_rcp_iflag_f32_e32 v4, v4
	v_add_u32_e32 v5, s2, v1
	v_mul_f32_e32 v4, 0x4f7ffffe, v4
	v_cvt_u32_f32_e32 v4, v4
	v_mul_lo_u32 v1, v3, v4
	v_mul_hi_u32 v1, v4, v1
	v_add_u32_e32 v1, v4, v1
	v_mul_hi_u32 v1, v5, v1
	v_mul_lo_u32 v3, v1, v2
	v_sub_u32_e32 v3, v5, v3
	v_add_u32_e32 v4, 1, v1
	v_cmp_ge_u32_e32 vcc, v3, v2
	s_nop 1
	v_cndmask_b32_e32 v1, v1, v4, vcc
	v_sub_u32_e32 v4, v3, v2
	v_cndmask_b32_e32 v3, v3, v4, vcc
	v_add_u32_e32 v4, 1, v1
	v_cmp_ge_u32_e32 vcc, v3, v2
	v_add_u32_e32 v3, 1, v5
	s_nop 0
	v_cndmask_b32_e32 v1, v1, v4, vcc
	v_mul_lo_u32 v4, v2, v1
	v_add_u32_e32 v2, v4, v2
	v_cmp_ne_u32_e32 vcc, v3, v2
	s_and_saveexec_b64 s[6:7], vcc
	s_xor_b64 s[6:7], exec, s[6:7]
	s_cbranch_execz .LBB0_659
	s_waitcnt lgkmcnt(0)
	v_mov_b32_e32 v0, 0x2000
	global_load_dword v0, v0, s[4:5] offset:1024 sc1
	s_add_u32 s18, s4, 0x2400
	s_addc_u32 s19, s5, 0
	s_waitcnt vmcnt(0)
	v_cmp_eq_u32_e32 vcc, v0, v1
	s_and_saveexec_b64 s[14:15], vcc
	s_cbranch_execz .LBB0_658
	s_add_u32 s16, s10, 0x4200
	s_addc_u32 s17, s11, 0
	s_mov_b32 s8, 1
	s_mov_b64 s[20:21], 0
	v_mov_b32_e32 v0, 0
	s_branch .LBB0_649

; __device__ __forceinline__ unsigned xb_add(unsigned* p, unsigned v) { return __hip_atomic_fetch_add(p, v, __ATOMIC_RELAXED, __HIP_MEMORY_SCOPE_AGENT); }
; __device__ __forceinline__ void xcd_barrier(const XcdBarrier& b) {
;     ...
;             __builtin_amdgcn_fence(__ATOMIC_ACQUIRE, "agent");
;             xb_add(&bar[XB_XGEN(b.x)], 1u);
;             asm volatile("s_waitcnt vmcnt(0)" ::: "memory");
.LBB0_676:
	s_or_b64 exec, exec, s[6:7]
	s_mov_b64 s[6:7], exec
	v_mbcnt_lo_u32_b32 v0, s6, 0
	v_mbcnt_hi_u32_b32 v0, s7, v0
	v_cmp_eq_u32_e32 vcc, 0, v0
	s_waitcnt vmcnt(0)
	s_and_saveexec_b64 s[14:15], vcc
	s_cbranch_execz .LBB0_678
	s_bcnt1_i32_b64 s2, s[6:7]
	v_mov_b32_e32 v0, 0x2000
	v_mov_b32_e32 v1, s2
	global_atomic_add v0, v1, s[4:5] offset:1024
.LBB0_678:
	s_or_b64 exec, exec, s[14:15]
	s_waitcnt vmcnt(0)

; __device__ __forceinline__ unsigned xb_add(unsigned* p, unsigned v) { return __hip_atomic_fetch_add(p, v, __ATOMIC_RELAXED, __HIP_MEMORY_SCOPE_AGENT); }
; __device__ __forceinline__ void xcd_barrier(const XcdBarrier& b) {
;     ...
;             __builtin_amdgcn_fence(__ATOMIC_ACQUIRE, "agent");
;             xb_add(&bar[XB_XGEN(b.x)], 1u);
;             asm volatile("s_waitcnt vmcnt(0)" ::: "memory");
.LBB0_746:
	s_or_b64 exec, exec, s[6:7]
	s_mov_b64 s[6:7], exec
	v_mbcnt_lo_u32_b32 v0, s6, 0
	v_mbcnt_hi_u32_b32 v0, s7, v0
	v_cmp_eq_u32_e32 vcc, 0, v0
	s_waitcnt vmcnt(0)
	s_and_saveexec_b64 s[14:15], vcc
	s_cbranch_execz .LBB0_748
	s_bcnt1_i32_b64 s2, s[6:7]
	v_mov_b32_e32 v0, 0x2000
	v_mov_b32_e32 v1, s2
	global_atomic_add v0, v1, s[4:5] offset:1024
.LBB0_748:
	s_or_b64 exec, exec, s[14:15]
	s_waitcnt vmcnt(0)

; __device__ __forceinline__ unsigned xb_add(unsigned* p, unsigned v) { return __hip_atomic_fetch_add(p, v, __ATOMIC_RELAXED, __HIP_MEMORY_SCOPE_AGENT); }
; __device__ __forceinline__ void xcd_barrier(const XcdBarrier& b) {
;     ...
;             __builtin_amdgcn_fence(__ATOMIC_ACQUIRE, "agent");
;             xb_add(&bar[XB_XGEN(b.x)], 1u);
;             asm volatile("s_waitcnt vmcnt(0)" ::: "memory");
.LBB0_806:
	s_or_b64 exec, exec, s[6:7]
	s_mov_b64 s[6:7], exec
	v_mbcnt_lo_u32_b32 v0, s6, 0
	v_mbcnt_hi_u32_b32 v0, s7, v0
	v_cmp_eq_u32_e32 vcc, 0, v0
	s_waitcnt vmcnt(0)
	s_and_saveexec_b64 s[14:15], vcc
	s_cbranch_execz .LBB0_808
	s_bcnt1_i32_b64 s2, s[6:7]
	v_mov_b32_e32 v0, 0x2000
	v_mov_b32_e32 v1, s2
	global_atomic_add v0, v1, s[4:5] offset:1024
.LBB0_808:
	s_or_b64 exec, exec, s[14:15]
	s_waitcnt vmcnt(0)

; __device__ __forceinline__ unsigned xb_add(unsigned* p, unsigned v) { return __hip_atomic_fetch_add(p, v, __ATOMIC_RELAXED, __HIP_MEMORY_SCOPE_AGENT); }
; __device__ __forceinline__ void xcd_barrier(const XcdBarrier& b) {
;     ...
;             __builtin_amdgcn_fence(__ATOMIC_ACQUIRE, "agent");
;             xb_add(&bar[XB_XGEN(b.x)], 1u);
;             asm volatile("s_waitcnt vmcnt(0)" ::: "memory");
.LBB0_908:
	s_or_b64 exec, exec, s[6:7]
	s_mov_b64 s[6:7], exec
	v_mbcnt_lo_u32_b32 v0, s6, 0
	v_mbcnt_hi_u32_b32 v0, s7, v0
	v_cmp_eq_u32_e32 vcc, 0, v0
	s_waitcnt vmcnt(0)
	s_and_saveexec_b64 s[14:15], vcc
	s_cbranch_execz .LBB0_910
	s_bcnt1_i32_b64 s2, s[6:7]
	v_mov_b32_e32 v0, 0x2000
	v_mov_b32_e32 v1, s2
	global_atomic_add v0, v1, s[4:5] offset:1024
.LBB0_910:
	s_or_b64 exec, exec, s[14:15]
	s_waitcnt vmcnt(0)
